# QK MFMA burst at priority 2 (fast-path blocks at 1 from their start)
# speedup vs baseline: 1.0042x; 1.0042x over previous
; template <int MODE, int DK, bool PASS2> ...
;     ...
;             if (active) {
;                 f32x16 s0, s1;
;                 if (MODE == M_FOX) {
;                     const LAS float* ct = (const LAS float*)(lds + F_CT + buf * 256) + 8 * g;
; #pragma unroll
;                     for (int q4 = 0; q4 < 4; ++q4) {
;                         const f32x4 a = *(const LAS f32x4*)(ct + (q4 >> 1) * 16 + (q4 & 1) * 4), b = *(const LAS f32x4*)(ct + 32 + (q4 >> 1) * 16 + (q4 & 1) * 4);
; #pragma unroll
;                         for (int e = 0; e < 4; ++e) { s0[q4 * 4 + e] = a[e]; s1[q4 * 4 + e] = b[e]; }
;                     }
;                 } else { s0 = (f32x16)(0.f); s1 = (f32x16)(0.f); }
;                 const LAS unsigned char* kb = lds + F_KB0 + buf * F_KBS + g * 16 + prow * KSTR;
;                 __builtin_amdgcn_s_setprio(1);
; #pragma unroll
;                 for (int kk = 0; kk < DK / 16; ++kk) {
;                     const bf16x8 a0 = *(const LAS bf16x8*)(kb + kk * 32);
;                     const bf16x8 a1 = *(const LAS bf16x8*)(kb + 32 * KSTR + kk * 32);
;                     s0 = mfma32(a0, qf[kk], s0); s1 = mfma32(a1, qf[kk], s1);
;                 }
;                 __builtin_amdgcn_s_setprio(0);
;                 const bool need_causal = pos_max > t_wmin;
;                 const bool need_bias = (MODE != M_FOX) && ((t_wmin - pos_max) < 128);
;                 const bool need_win = (MODE == M_WIN) && (t_wmax - pos_min >= 512);
;                 if (!PASS2 && !(need_causal || need_bias || need_win)) {
;                     float mx = fmaxf(s0[0], s1[0]);
; #pragma unroll
;                     for (int r = 1; r < 16; ++r) mx = fmax3(mx, s0[r], s1[r]);
;                     if (MODE == M_SLC) mx = selbit ? mx : NEG;
;                     mx = xhalf_max(mx);
;                     const float mxs = mx * sl2;
;                     const float mn = (mxs > m_run + 8.0f) ? mxs : m_run;
;                     const float alpha = fexp2(m_run - mn);
;                     m_run = mn;
;                     float nm = -mn;
;                     if (MODE == M_SLC) nm = selbit ? nm : -__builtin_inff();
;                     float ps0 = 0.f, ps1 = 0.f;
; #pragma unroll
;                     for (int r = 0; r < 16; ++r) {
;                         s0[r] = fexp2(__builtin_fmaf(s0[r], sl2, nm)); s1[r] = fexp2(__builtin_fmaf(s1[r], sl2, nm));
.LBB0_942:
	s_sub_i32 s24, s87, 63
	v_cmp_le_i32_e32 vcc, s24, v227
	v_mov_b32_e32 v2, 0
	s_and_saveexec_b64 s[50:51], vcc
	s_cbranch_execz .LBB0_954
	v_lshl_add_u32 v2, s86, 8, v229
	ds_read_b128 v[98:101], v2
	ds_read_b128 v[102:105], v2 offset:16
	ds_read_b128 v[82:85], v2 offset:128
	ds_read_b128 v[86:89], v2 offset:144
	ds_read_b128 v[106:109], v2 offset:64
	ds_read_b128 v[110:113], v2 offset:80
	ds_read_b128 v[90:93], v2 offset:192
	ds_read_b128 v[94:97], v2 offset:208
	s_mul_i32 s24, s86, 0x4400
	v_add_u32_e32 v2, s24, v230
	s_setprio 2
	ds_read_b128 v[4:7], v2
	ds_read_b128 v[8:11], v2 offset:32
	s_waitcnt lgkmcnt(1)
	v_mfma_f32_32x32x16_bf16 v[98:113], v[4:7], v[146:149], v[98:113]
	ds_read_b128 v[4:7], v2 offset:8704
	ds_read_b128 v[12:15], v2 offset:8736
	s_waitcnt lgkmcnt(1)
	v_mfma_f32_32x32x16_bf16 v[82:97], v[4:7], v[146:149], v[82:97]
	v_mfma_f32_32x32x16_bf16 v[98:113], v[8:11], v[150:153], v[98:113]
	ds_read_b128 v[4:7], v2 offset:64
	ds_read_b128 v[8:11], v2 offset:96
	s_waitcnt lgkmcnt(2)
	v_mfma_f32_32x32x16_bf16 v[82:97], v[12:15], v[150:153], v[82:97]
	s_waitcnt lgkmcnt(1)
	v_mfma_f32_32x32x16_bf16 v[98:113], v[4:7], v[154:157], v[98:113]
	ds_read_b128 v[4:7], v2 offset:8768
	ds_read_b128 v[12:15], v2 offset:8800
	s_waitcnt lgkmcnt(1)
	v_mfma_f32_32x32x16_bf16 v[82:97], v[4:7], v[154:157], v[82:97]
	v_mfma_f32_32x32x16_bf16 v[98:113], v[8:11], v[158:161], v[98:113]
	ds_read_b128 v[4:7], v2 offset:128
	ds_read_b128 v[8:11], v2 offset:160
	s_waitcnt lgkmcnt(2)
	v_mfma_f32_32x32x16_bf16 v[82:97], v[12:15], v[158:161], v[82:97]
	s_waitcnt lgkmcnt(1)
	v_mfma_f32_32x32x16_bf16 v[98:113], v[4:7], v[162:165], v[98:113]
	ds_read_b128 v[4:7], v2 offset:8832
	ds_read_b128 v[12:15], v2 offset:8864
	s_waitcnt lgkmcnt(1)
	v_mfma_f32_32x32x16_bf16 v[82:97], v[4:7], v[162:165], v[82:97]
	v_mfma_f32_32x32x16_bf16 v[98:113], v[8:11], v[166:169], v[98:113]
	ds_read_b128 v[4:7], v2 offset:192
	ds_read_b128 v[8:11], v2 offset:224
	s_waitcnt lgkmcnt(2)
	v_mfma_f32_32x32x16_bf16 v[82:97], v[12:15], v[166:169], v[82:97]
	s_waitcnt lgkmcnt(1)
	v_mfma_f32_32x32x16_bf16 v[98:113], v[4:7], v[170:173], v[98:113]
	ds_read_b128 v[4:7], v2 offset:8896
	ds_read_b128 v[12:15], v2 offset:8928
	s_waitcnt lgkmcnt(1)
	v_mfma_f32_32x32x16_bf16 v[82:97], v[4:7], v[170:173], v[82:97]
	v_mfma_f32_32x32x16_bf16 v[98:113], v[8:11], v[174:177], v[98:113]
	s_waitcnt lgkmcnt(0)
	v_mfma_f32_32x32x16_bf16 v[82:97], v[12:15], v[174:177], v[82:97]
	s_setprio 0
	v_cmp_le_i32_e32 vcc, s87, v216
	v_add_f32_e32 v2, 0x41000000, v239
	s_and_saveexec_b64 s[52:53], vcc
	s_xor_b64 s[52:53], exec, s[52:53]
	s_cbranch_execz .LBB0_947
	s_cmp_eq_u64 s[52:53], 0
	s_cbranch_scc1 .Lfast_fox
	s_nop 3
	v_max_f32_e32 v4, v98, v98
	s_nop 0
	v_max_f32_e32 v5, v82, v82
	v_max_f32_e32 v4, v4, v5
	v_max3_f32 v4, v4, v99, v83
	s_nop 0
	v_max3_f32 v4, v4, v100, v84
	s_nop 0
	v_max3_f32 v4, v4, v101, v85
	s_nop 0
	v_max3_f32 v4, v4, v102, v86
	s_nop 0
	v_max3_f32 v4, v4, v103, v87
	s_nop 0
	v_max3_f32 v4, v4, v104, v88
	s_nop 0
	v_max3_f32 v4, v4, v105, v89
	s_nop 0
	v_max3_f32 v4, v4, v106, v90
	s_nop 0
	v_max3_f32 v4, v4, v107, v91
	s_nop 0
	v_max3_f32 v4, v4, v108, v92
	s_nop 0
	v_max3_f32 v4, v4, v109, v93
	s_nop 0
	v_max3_f32 v4, v4, v110, v94
	s_nop 0
	v_max3_f32 v4, v4, v111, v95
	s_nop 0
	v_max3_f32 v4, v4, v112, v96
	s_nop 0
	v_max3_f32 v4, v4, v113, v97
	s_nop 0
	v_mov_b32_e32 v5, v4
	s_nop 1
	v_permlane32_swap_b32_e32 v4, v5
	v_max_f32_e32 v5, v5, v5
	v_max_f32_e32 v4, v4, v4
	v_max_f32_e32 v4, v4, v5
	v_mul_f32_e32 v4, 0x3e0293ee, v4
	v_cmp_gt_f32_e32 vcc, v4, v2
	s_nop 1
	v_cndmask_b32_e32 v4, v239, v4, vcc
	v_sub_f32_e32 v2, v239, v4
	v_exp_f32_e32 v2, v2
	s_nop 0
	v_cmp_neq_f32_e32 vcc, 1.0, v2
	s_cbranch_vccz .LBB0_946
	v_pk_mul_f32 v[80:81], v[80:81], v[2:3] op_sel_hi:[1,0]
	v_pk_mul_f32 v[78:79], v[78:79], v[2:3] op_sel_hi:[1,0]
	v_pk_mul_f32 v[76:77], v[76:77], v[2:3] op_sel_hi:[1,0]
	v_pk_mul_f32 v[74:75], v[74:75], v[2:3] op_sel_hi:[1,0]
	v_pk_mul_f32 v[72:73], v[72:73], v[2:3] op_sel_hi:[1,0]
	v_pk_mul_f32 v[70:71], v[70:71], v[2:3] op_sel_hi:[1,0]
	v_pk_mul_f32 v[68:69], v[68:69], v[2:3] op_sel_hi:[1,0]
	v_pk_mul_f32 v[66:67], v[66:67], v[2:3] op_sel_hi:[1,0]
	v_pk_mul_f32 v[64:65], v[64:65], v[2:3] op_sel_hi:[1,0]
	v_pk_mul_f32 v[62:63], v[62:63], v[2:3] op_sel_hi:[1,0]
	v_pk_mul_f32 v[60:61], v[60:61], v[2:3] op_sel_hi:[1,0]
	v_pk_mul_f32 v[58:59], v[58:59], v[2:3] op_sel_hi:[1,0]
	v_pk_mul_f32 v[56:57], v[56:57], v[2:3] op_sel_hi:[1,0]
	v_pk_mul_f32 v[54:55], v[54:55], v[2:3] op_sel_hi:[1,0]
	v_pk_mul_f32 v[52:53], v[52:53], v[2:3] op_sel_hi:[1,0]
	v_pk_mul_f32 v[50:51], v[50:51], v[2:3] op_sel_hi:[1,0]
	v_pk_mul_f32 v[48:49], v[48:49], v[2:3] op_sel_hi:[1,0]
	v_pk_mul_f32 v[46:47], v[46:47], v[2:3] op_sel_hi:[1,0]
	v_pk_mul_f32 v[44:45], v[44:45], v[2:3] op_sel_hi:[1,0]
	v_pk_mul_f32 v[42:43], v[42:43], v[2:3] op_sel_hi:[1,0]
	v_pk_mul_f32 v[40:41], v[40:41], v[2:3] op_sel_hi:[1,0]
	v_pk_mul_f32 v[38:39], v[38:39], v[2:3] op_sel_hi:[1,0]
	v_pk_mul_f32 v[36:37], v[36:37], v[2:3] op_sel_hi:[1,0]
	v_pk_mul_f32 v[34:35], v[34:35], v[2:3] op_sel_hi:[1,0]
	v_pk_mul_f32 v[32:33], v[32:33], v[2:3] op_sel_hi:[1,0]
	v_pk_mul_f32 v[30:31], v[30:31], v[2:3] op_sel_hi:[1,0]
	v_pk_mul_f32 v[28:29], v[28:29], v[2:3] op_sel_hi:[1,0]
	v_pk_mul_f32 v[26:27], v[26:27], v[2:3] op_sel_hi:[1,0]
	v_pk_mul_f32 v[24:25], v[24:25], v[2:3] op_sel_hi:[1,0]
	v_pk_mul_f32 v[22:23], v[22:23], v[2:3] op_sel_hi:[1,0]
	v_pk_mul_f32 v[20:21], v[20:21], v[2:3] op_sel_hi:[1,0]
	v_pk_mul_f32 v[18:19], v[18:19], v[2:3] op_sel_hi:[1,0]

; #define LAS __attribute__((address_space(3)))
; __device__ __forceinline__ float fexp2(float x) { return __builtin_amdgcn_exp2f(x); }
; __device__ __forceinline__ f32x16 mfma32(bf16x8 a, bf16x8 b, f32x16 c) { return __builtin_amdgcn_mfma_f32_32x32x16_bf16(a, b, c, 0, 0, 0); }
; template <int MODE, int DK, bool PASS2> ...
;     ...
;                 const LAS unsigned char* kb = lds + F_KB0 + buf * F_KBS + g * 16 + prow * KSTR;
;                 __builtin_amdgcn_s_setprio(1);
; #pragma unroll
;                 for (int kk = 0; kk < DK / 16; ++kk) {
;                     const bf16x8 a0 = *(const LAS bf16x8*)(kb + kk * 32);
;                     const bf16x8 a1 = *(const LAS bf16x8*)(kb + 32 * KSTR + kk * 32);
;                     s0 = mfma32(a0, qf[kk], s0); s1 = mfma32(a1, qf[kk], s1);
;                 }
;                 __builtin_amdgcn_s_setprio(0);
;                 const bool need_causal = pos_max > t_wmin;
;                 const bool need_bias = (MODE != M_FOX) && ((t_wmin - pos_max) < 128);
;                 const bool need_win = (MODE == M_WIN) && (t_wmax - pos_min >= 512);
;                 if (!PASS2 && !(need_causal || need_bias || need_win)) {
;                     float mx = fmaxf(s0[0], s1[0]);
; #pragma unroll
;                     for (int r = 1; r < 16; ++r) mx = fmax3(mx, s0[r], s1[r]);
;                     if (MODE == M_SLC) mx = selbit ? mx : NEG;
;                     mx = xhalf_max(mx);
;                     const float mxs = mx * sl2;
;                     const float mn = (mxs > m_run + 8.0f) ? mxs : m_run;
;                     const float alpha = fexp2(m_run - mn);
;                     m_run = mn;
;                     float nm = -mn;
;                     if (MODE == M_SLC) nm = selbit ? nm : -__builtin_inff();
;                     float ps0 = 0.f, ps1 = 0.f;
; #pragma unroll
;                     for (int r = 0; r < 16; ++r) {
;                         s0[r] = fexp2(__builtin_fmaf(s0[r], sl2, nm)); s1[r] = fexp2(__builtin_fmaf(s1[r], sl2, nm));
;                         ps0 += s0[r]; ps1 += s1[r];
;                     }
;                     l_run = l_run * alpha + (ps0 + ps1);
;                     if (__builtin_amdgcn_ballot_w64(alpha != 1.0f) != 0ull) {
; #pragma unroll
;                         for (int db = 0; db < 4; ++db)
; #pragma unroll
;                             for (int r = 0; r < 16; ++r) O[db][r] *= alpha;
.LBB0_2131:
	s_mul_i32 s4, s58, 0x4400
	v_add_u32_e32 v16, s4, v202
	s_setprio 2
	ds_read_b128 v[4:7], v16
	ds_read_b128 v[8:11], v16 offset:32
	s_waitcnt lgkmcnt(1)
	v_mfma_f32_32x32x16_bf16 v[82:97], v[4:7], v[114:117], 0
	ds_read_b128 v[4:7], v16 offset:4608
	ds_read_b128 v[12:15], v16 offset:4640
	s_waitcnt lgkmcnt(1)
	v_mfma_f32_32x32x16_bf16 v[98:113], v[4:7], v[114:117], 0
	v_mfma_f32_32x32x16_bf16 v[82:97], v[8:11], v[118:121], v[82:97]
	ds_read_b128 v[4:7], v16 offset:64
	ds_read_b128 v[8:11], v16 offset:96
	s_waitcnt lgkmcnt(2)
	v_mfma_f32_32x32x16_bf16 v[98:113], v[12:15], v[118:121], v[98:113]
	s_waitcnt lgkmcnt(1)
	v_mfma_f32_32x32x16_bf16 v[82:97], v[4:7], v[122:125], v[82:97]
	ds_read_b128 v[4:7], v16 offset:4672
	ds_read_b128 v[12:15], v16 offset:4704
	s_waitcnt lgkmcnt(1)
	v_mfma_f32_32x32x16_bf16 v[98:113], v[4:7], v[122:125], v[98:113]
	v_mfma_f32_32x32x16_bf16 v[82:97], v[8:11], v[126:129], v[82:97]
	s_waitcnt lgkmcnt(0)
	v_mfma_f32_32x32x16_bf16 v[98:113], v[12:15], v[126:129], v[98:113]
	s_setprio 0
	v_add_u32_e32 v4, s8, v196
	v_cmp_le_i32_e32 vcc, s57, v193
	v_cmp_lt_i32_e64 s[6:7], s52, v4
	v_cmp_gt_i32_e64 s[4:5], s51, v4
	s_and_b64 s[6:7], vcc, s[6:7]
	v_add_f32_e32 v208, 0x41000000, v178
	s_and_saveexec_b64 s[28:29], s[6:7]
	s_xor_b64 s[6:7], exec, s[28:29]
	s_cbranch_execz .LBB0_2135
	s_cmp_eq_u64 s[6:7], 0
	s_cbranch_scc1 .Lfast_diff
	s_nop 1
	v_max_f32_e32 v4, v98, v98
	v_max_f32_e32 v5, v82, v82
	v_max_f32_e32 v4, v5, v4
	v_max3_f32 v4, v4, v83, v99
	s_nop 0
	v_max3_f32 v4, v4, v84, v100
	s_nop 0
	v_max3_f32 v4, v4, v85, v101
	s_nop 0
	v_max3_f32 v4, v4, v86, v102
	s_nop 0
	v_max3_f32 v4, v4, v87, v103
	s_nop 0
	v_max3_f32 v4, v4, v88, v104
	s_nop 0
	v_max3_f32 v4, v4, v89, v105
	s_nop 0
	v_max3_f32 v4, v4, v90, v106
	s_nop 0
	v_max3_f32 v4, v4, v91, v107
	s_nop 0
	v_max3_f32 v4, v4, v92, v108
	s_nop 0
	v_max3_f32 v4, v4, v93, v109
	s_nop 0
	v_max3_f32 v4, v4, v94, v110
	s_nop 0
	v_max3_f32 v4, v4, v95, v111
	s_nop 0
	v_max3_f32 v4, v4, v96, v112
	s_nop 0
	v_max3_f32 v4, v4, v97, v113
	s_nop 0
	v_mov_b32_e32 v5, v4
	s_nop 1
	v_permlane32_swap_b32_e32 v4, v5
	v_max_f32_e32 v5, v5, v5
	v_max_f32_e32 v4, v4, v4
	v_max_f32_e32 v4, v4, v5
	v_mul_f32_e32 v4, 0x3e38aa3b, v4
	v_cmp_gt_f32_e32 vcc, v4, v208
	s_nop 1
	v_cndmask_b32_e32 v207, v178, v4, vcc
	v_sub_f32_e32 v4, v178, v207
	v_exp_f32_e32 v178, v4
	s_nop 0
	v_cmp_neq_f32_e32 vcc, 1.0, v178
	s_cbranch_vccz .LBB0_2134
	v_pk_mul_f32 v[80:81], v[80:81], v[178:179] op_sel_hi:[1,0]
	v_pk_mul_f32 v[78:79], v[78:79], v[178:179] op_sel_hi:[1,0]
	v_pk_mul_f32 v[76:77], v[76:77], v[178:179] op_sel_hi:[1,0]
	v_pk_mul_f32 v[74:75], v[74:75], v[178:179] op_sel_hi:[1,0]
	v_pk_mul_f32 v[72:73], v[72:73], v[178:179] op_sel_hi:[1,0]
	v_pk_mul_f32 v[70:71], v[70:71], v[178:179] op_sel_hi:[1,0]
	v_pk_mul_f32 v[68:69], v[68:69], v[178:179] op_sel_hi:[1,0]
	v_pk_mul_f32 v[66:67], v[66:67], v[178:179] op_sel_hi:[1,0]
	v_pk_mul_f32 v[64:65], v[64:65], v[178:179] op_sel_hi:[1,0]
	v_pk_mul_f32 v[62:63], v[62:63], v[178:179] op_sel_hi:[1,0]
	v_pk_mul_f32 v[60:61], v[60:61], v[178:179] op_sel_hi:[1,0]
	v_pk_mul_f32 v[58:59], v[58:59], v[178:179] op_sel_hi:[1,0]
	v_pk_mul_f32 v[56:57], v[56:57], v[178:179] op_sel_hi:[1,0]
	v_pk_mul_f32 v[54:55], v[54:55], v[178:179] op_sel_hi:[1,0]
	v_pk_mul_f32 v[52:53], v[52:53], v[178:179] op_sel_hi:[1,0]
	v_pk_mul_f32 v[50:51], v[50:51], v[178:179] op_sel_hi:[1,0]
	v_pk_mul_f32 v[48:49], v[48:49], v[178:179] op_sel_hi:[1,0]
	v_pk_mul_f32 v[46:47], v[46:47], v[178:179] op_sel_hi:[1,0]
	v_pk_mul_f32 v[44:45], v[44:45], v[178:179] op_sel_hi:[1,0]
	v_pk_mul_f32 v[42:43], v[42:43], v[178:179] op_sel_hi:[1,0]
	v_pk_mul_f32 v[40:41], v[40:41], v[178:179] op_sel_hi:[1,0]
	v_pk_mul_f32 v[38:39], v[38:39], v[178:179] op_sel_hi:[1,0]
	v_pk_mul_f32 v[36:37], v[36:37], v[178:179] op_sel_hi:[1,0]
	v_pk_mul_f32 v[34:35], v[34:35], v[178:179] op_sel_hi:[1,0]
	v_pk_mul_f32 v[32:33], v[32:33], v[178:179] op_sel_hi:[1,0]
	v_pk_mul_f32 v[30:31], v[30:31], v[178:179] op_sel_hi:[1,0]
	v_pk_mul_f32 v[28:29], v[28:29], v[178:179] op_sel_hi:[1,0]
	v_pk_mul_f32 v[26:27], v[26:27], v[178:179] op_sel_hi:[1,0]
	v_pk_mul_f32 v[24:25], v[24:25], v[178:179] op_sel_hi:[1,0]
	v_pk_mul_f32 v[22:23], v[22:23], v[178:179] op_sel_hi:[1,0]
	v_pk_mul_f32 v[20:21], v[20:21], v[178:179] op_sel_hi:[1,0]
	v_pk_mul_f32 v[18:19], v[18:19], v[178:179] op_sel_hi:[1,0]

; template <int MODE, int DK, bool PASS2> ...
;     ...
;             const int kv0 = j * 64;
;             const int pos_min = (MODE == M_CMP) ? 16 * kv0 + 31 : kv0;
;             const int pos_max = (MODE == M_CMP) ? 16 * (kv0 + 63) + 31 : kv0 + 63;
;             bool active = pos_min <= t_wmax;
;             if (MODE == M_WIN) active = active && (t_wmin - pos_max < 512);
;             bool selbit = true;
;             if (MODE == M_SLC) {
;                 selbit = ((((const LAS unsigned*)impw)[j >> 5] >> (j & 31)) & 1u) != 0u;
;                 active = active && (__builtin_amdgcn_ballot_w64(selbit) != 0ull);
;             }
;             if (active) {
;                 f32x16 s0, s1;
;                 if (MODE == M_FOX) {
;                     const LAS float* ct = (const LAS float*)(lds + F_CT + buf * 256) + 8 * g;
; #pragma unroll
;                     for (int q4 = 0; q4 < 4; ++q4) {
;                         const f32x4 a = *(const LAS f32x4*)(ct + (q4 >> 1) * 16 + (q4 & 1) * 4), b = *(const LAS f32x4*)(ct + 32 + (q4 >> 1) * 16 + (q4 & 1) * 4);
; #pragma unroll
;                         for (int e = 0; e < 4; ++e) { s0[q4 * 4 + e] = a[e]; s1[q4 * 4 + e] = b[e]; }
;                     }
;                 } else { s0 = (f32x16)(0.f); s1 = (f32x16)(0.f); }
;                 const LAS unsigned char* kb = lds + F_KB0 + buf * F_KBS + g * 16 + prow * KSTR;
;                 __builtin_amdgcn_s_setprio(1);
; #pragma unroll
;                 for (int kk = 0; kk < DK / 16; ++kk) {
;                     const bf16x8 a0 = *(const LAS bf16x8*)(kb + kk * 32);
;                     const bf16x8 a1 = *(const LAS bf16x8*)(kb + 32 * KSTR + kk * 32);
;                     s0 = mfma32(a0, qf[kk], s0); s1 = mfma32(a1, qf[kk], s1);
;                 }
;                 __builtin_amdgcn_s_setprio(0);
;                 const bool need_causal = pos_max > t_wmin;
;                 const bool need_bias = (MODE != M_FOX) && ((t_wmin - pos_max) < 128);
;                 const bool need_win = (MODE == M_WIN) && (t_wmax - pos_min >= 512);
;                 if (!PASS2 && !(need_causal || need_bias || need_win)) {
;                     float mx = fmaxf(s0[0], s1[0]);
; #pragma unroll
;                     for (int r = 1; r < 16; ++r) mx = fmax3(mx, s0[r], s1[r]);
;                     if (MODE == M_SLC) mx = selbit ? mx : NEG;
;                     mx = xhalf_max(mx);
.LBB0_2164:
	v_add_u32_e32 v2, 0xffffffa2, v201
	v_cmp_le_i32_e32 vcc, s88, v192
	v_cmp_gt_i32_e64 s[4:5], s82, v2
	s_and_b64 s[4:5], vcc, s[4:5]
	s_and_saveexec_b64 s[68:69], s[4:5]
	s_cbranch_execz .LBB0_2240
	s_mul_i32 s5, s89, 0x4400
	s_add_i32 s4, s88, 63
	v_add_u32_e32 v16, s5, v200
	s_setprio 2
	ds_read_b128 v[4:7], v16
	ds_read_b128 v[8:11], v16 offset:32
	s_waitcnt lgkmcnt(1)
	v_mfma_f32_32x32x16_bf16 v[98:113], v[4:7], v[114:117], 0
	ds_read_b128 v[4:7], v16 offset:8704
	ds_read_b128 v[12:15], v16 offset:8736
	s_waitcnt lgkmcnt(1)
	v_mfma_f32_32x32x16_bf16 v[82:97], v[4:7], v[114:117], 0
	v_mfma_f32_32x32x16_bf16 v[98:113], v[8:11], v[118:121], v[98:113]
	ds_read_b128 v[4:7], v16 offset:64
	ds_read_b128 v[8:11], v16 offset:96
	s_waitcnt lgkmcnt(2)
	v_mfma_f32_32x32x16_bf16 v[82:97], v[12:15], v[118:121], v[82:97]
	s_waitcnt lgkmcnt(1)
	v_mfma_f32_32x32x16_bf16 v[98:113], v[4:7], v[122:125], v[98:113]
	ds_read_b128 v[4:7], v16 offset:8768
	ds_read_b128 v[12:15], v16 offset:8800
	s_waitcnt lgkmcnt(1)
	v_mfma_f32_32x32x16_bf16 v[82:97], v[4:7], v[122:125], v[82:97]
	v_mfma_f32_32x32x16_bf16 v[98:113], v[8:11], v[126:129], v[98:113]
	ds_read_b128 v[4:7], v16 offset:128
	ds_read_b128 v[8:11], v16 offset:160
	s_waitcnt lgkmcnt(2)
	v_mfma_f32_32x32x16_bf16 v[82:97], v[12:15], v[126:129], v[82:97]
	s_waitcnt lgkmcnt(1)
	v_mfma_f32_32x32x16_bf16 v[98:113], v[4:7], v[130:133], v[98:113]
	ds_read_b128 v[4:7], v16 offset:8832
	ds_read_b128 v[12:15], v16 offset:8864
	s_waitcnt lgkmcnt(1)
	v_mfma_f32_32x32x16_bf16 v[82:97], v[4:7], v[130:133], v[82:97]
	v_mfma_f32_32x32x16_bf16 v[98:113], v[8:11], v[134:137], v[98:113]
	ds_read_b128 v[4:7], v16 offset:192
	ds_read_b128 v[8:11], v16 offset:224
	s_waitcnt lgkmcnt(2)
	v_mfma_f32_32x32x16_bf16 v[82:97], v[12:15], v[134:137], v[82:97]
	s_waitcnt lgkmcnt(1)
	v_mfma_f32_32x32x16_bf16 v[98:113], v[4:7], v[138:141], v[98:113]
	ds_read_b128 v[4:7], v16 offset:8896
	ds_read_b128 v[12:15], v16 offset:8928
	s_waitcnt lgkmcnt(1)
	v_mfma_f32_32x32x16_bf16 v[82:97], v[4:7], v[138:141], v[82:97]
	v_mfma_f32_32x32x16_bf16 v[98:113], v[8:11], v[142:145], v[98:113]
	s_waitcnt lgkmcnt(0)
	v_mfma_f32_32x32x16_bf16 v[82:97], v[12:15], v[142:145], v[82:97]
	s_setprio 0
	v_cmp_gt_i32_e32 vcc, s4, v190
	v_cmp_lt_i32_e64 s[6:7], s45, v201
	v_cmp_gt_i32_e64 s[4:5], s76, v2
	s_or_b64 s[8:9], vcc, s[6:7]
	s_nor_b64 s[8:9], s[8:9], s[4:5]
	v_add_f32_e32 v2, 0x41000000, v207
	s_and_saveexec_b64 s[10:11], s[8:9]
	s_xor_b64 s[8:9], exec, s[10:11]
	s_cbranch_execz .LBB0_2169
	s_cmp_eq_u64 s[8:9], 0
	s_cbranch_scc1 .Lfast_win
	s_nop 1
	v_max_f32_e32 v4, v82, v82
	v_max_f32_e32 v5, v98, v98
	v_max_f32_e32 v4, v5, v4
	v_max3_f32 v4, v4, v99, v83
	s_nop 0
	v_max3_f32 v4, v4, v100, v84
	s_nop 0
	v_max3_f32 v4, v4, v101, v85
	s_nop 0
	v_max3_f32 v4, v4, v102, v86
	s_nop 0
	v_max3_f32 v4, v4, v103, v87
	s_nop 0
	v_max3_f32 v4, v4, v104, v88
	s_nop 0
	v_max3_f32 v4, v4, v105, v89
	s_nop 0
	v_max3_f32 v4, v4, v106, v90
	s_nop 0
	v_max3_f32 v4, v4, v107, v91
	s_nop 0
	v_max3_f32 v4, v4, v108, v92
	s_nop 0
	v_max3_f32 v4, v4, v109, v93
	s_nop 0
	v_max3_f32 v4, v4, v110, v94
	s_nop 0
	v_max3_f32 v4, v4, v111, v95
	s_nop 0
	v_max3_f32 v4, v4, v112, v96
	s_nop 0
	v_max3_f32 v4, v4, v113, v97
	s_nop 0
	v_mov_b32_e32 v5, v4
	s_nop 1
	v_permlane32_swap_b32_e32 v4, v5
	v_max_f32_e32 v5, v5, v5
	v_max_f32_e32 v4, v4, v4
	v_max_f32_e32 v4, v4, v5
	v_mul_f32_e32 v4, 0x3e0293ee, v4
	v_cmp_gt_f32_e32 vcc, v4, v2
	s_nop 1
	v_cndmask_b32_e32 v208, v207, v4, vcc
	v_sub_f32_e32 v2, v207, v208
	v_exp_f32_e32 v2, v2
	s_nop 0
	v_cmp_neq_f32_e32 vcc, 1.0, v2
	s_cbranch_vccz .LBB0_2168
	v_pk_mul_f32 v[80:81], v[80:81], v[2:3] op_sel_hi:[1,0]
	v_pk_mul_f32 v[78:79], v[78:79], v[2:3] op_sel_hi:[1,0]
	v_pk_mul_f32 v[76:77], v[76:77], v[2:3] op_sel_hi:[1,0]
	v_pk_mul_f32 v[74:75], v[74:75], v[2:3] op_sel_hi:[1,0]
	v_pk_mul_f32 v[72:73], v[72:73], v[2:3] op_sel_hi:[1,0]
	v_pk_mul_f32 v[70:71], v[70:71], v[2:3] op_sel_hi:[1,0]
	v_pk_mul_f32 v[68:69], v[68:69], v[2:3] op_sel_hi:[1,0]
	v_pk_mul_f32 v[66:67], v[66:67], v[2:3] op_sel_hi:[1,0]
	v_pk_mul_f32 v[64:65], v[64:65], v[2:3] op_sel_hi:[1,0]
	v_pk_mul_f32 v[62:63], v[62:63], v[2:3] op_sel_hi:[1,0]
	v_pk_mul_f32 v[60:61], v[60:61], v[2:3] op_sel_hi:[1,0]
	v_pk_mul_f32 v[58:59], v[58:59], v[2:3] op_sel_hi:[1,0]
	v_pk_mul_f32 v[56:57], v[56:57], v[2:3] op_sel_hi:[1,0]
	v_pk_mul_f32 v[54:55], v[54:55], v[2:3] op_sel_hi:[1,0]
	v_pk_mul_f32 v[52:53], v[52:53], v[2:3] op_sel_hi:[1,0]
	v_pk_mul_f32 v[50:51], v[50:51], v[2:3] op_sel_hi:[1,0]
	v_pk_mul_f32 v[48:49], v[48:49], v[2:3] op_sel_hi:[1,0]
	v_pk_mul_f32 v[46:47], v[46:47], v[2:3] op_sel_hi:[1,0]
	v_pk_mul_f32 v[44:45], v[44:45], v[2:3] op_sel_hi:[1,0]
	v_pk_mul_f32 v[42:43], v[42:43], v[2:3] op_sel_hi:[1,0]
	v_pk_mul_f32 v[40:41], v[40:41], v[2:3] op_sel_hi:[1,0]
	v_pk_mul_f32 v[38:39], v[38:39], v[2:3] op_sel_hi:[1,0]
	v_pk_mul_f32 v[36:37], v[36:37], v[2:3] op_sel_hi:[1,0]
	v_pk_mul_f32 v[34:35], v[34:35], v[2:3] op_sel_hi:[1,0]
	v_pk_mul_f32 v[32:33], v[32:33], v[2:3] op_sel_hi:[1,0]
	v_pk_mul_f32 v[30:31], v[30:31], v[2:3] op_sel_hi:[1,0]
	v_pk_mul_f32 v[28:29], v[28:29], v[2:3] op_sel_hi:[1,0]
	v_pk_mul_f32 v[26:27], v[26:27], v[2:3] op_sel_hi:[1,0]
	v_pk_mul_f32 v[24:25], v[24:25], v[2:3] op_sel_hi:[1,0]
	v_pk_mul_f32 v[22:23], v[22:23], v[2:3] op_sel_hi:[1,0]
	v_pk_mul_f32 v[20:21], v[20:21], v[2:3] op_sel_hi:[1,0]
	v_pk_mul_f32 v[18:19], v[18:19], v[2:3] op_sel_hi:[1,0]

; template <int MODE, int DK, bool PASS2> ...
;     ...
;             if (active) {
;                 f32x16 s0, s1;
;                 if (MODE == M_FOX) {
;                     const LAS float* ct = (const LAS float*)(lds + F_CT + buf * 256) + 8 * g;
; #pragma unroll
;                     for (int q4 = 0; q4 < 4; ++q4) {
;                         const f32x4 a = *(const LAS f32x4*)(ct + (q4 >> 1) * 16 + (q4 & 1) * 4), b = *(const LAS f32x4*)(ct + 32 + (q4 >> 1) * 16 + (q4 & 1) * 4);
; #pragma unroll
;                         for (int e = 0; e < 4; ++e) { s0[q4 * 4 + e] = a[e]; s1[q4 * 4 + e] = b[e]; }
;                     }
;                 } else { s0 = (f32x16)(0.f); s1 = (f32x16)(0.f); }
;                 const LAS unsigned char* kb = lds + F_KB0 + buf * F_KBS + g * 16 + prow * KSTR;
;                 __builtin_amdgcn_s_setprio(1);
; #pragma unroll
;                 for (int kk = 0; kk < DK / 16; ++kk) {
;                     const bf16x8 a0 = *(const LAS bf16x8*)(kb + kk * 32);
;                     const bf16x8 a1 = *(const LAS bf16x8*)(kb + 32 * KSTR + kk * 32);
;                     s0 = mfma32(a0, qf[kk], s0); s1 = mfma32(a1, qf[kk], s1);
;                 }
;                 __builtin_amdgcn_s_setprio(0);
;                 const bool need_causal = pos_max > t_wmin;
;                 const bool need_bias = (MODE != M_FOX) && ((t_wmin - pos_max) < 128);
;                 const bool need_win = (MODE == M_WIN) && (t_wmax - pos_min >= 512);
;                 if (!PASS2 && !(need_causal || need_bias || need_win)) {
;                     float mx = fmaxf(s0[0], s1[0]);
; #pragma unroll
;                     for (int r = 1; r < 16; ++r) mx = fmax3(mx, s0[r], s1[r]);
;                     if (MODE == M_SLC) mx = selbit ? mx : NEG;
;                     mx = xhalf_max(mx);
;                     const float mxs = mx * sl2;
;                     const float mn = (mxs > m_run + 8.0f) ? mxs : m_run;
;                     const float alpha = fexp2(m_run - mn);
;                     m_run = mn;
;                     float nm = -mn;
;                     if (MODE == M_SLC) nm = selbit ? nm : -__builtin_inff();
;                     float ps0 = 0.f, ps1 = 0.f;
; #pragma unroll
;                     for (int r = 0; r < 16; ++r) {
;                         s0[r] = fexp2(__builtin_fmaf(s0[r], sl2, nm)); s1[r] = fexp2(__builtin_fmaf(s1[r], sl2, nm));
.LBB0_2269:
	s_mul_i32 s4, s39, 0x4400
	v_add_u32_e32 v2, s4, v243
	s_setprio 2
	ds_read_b128 v[4:7], v2
	ds_read_b128 v[8:11], v2 offset:32
	s_waitcnt lgkmcnt(1)
	v_mfma_f32_32x32x16_bf16 v[82:97], v[4:7], v[114:117], 0
	ds_read_b128 v[4:7], v2 offset:8704
	ds_read_b128 v[12:15], v2 offset:8736
	s_waitcnt lgkmcnt(1)
	v_mfma_f32_32x32x16_bf16 v[98:113], v[4:7], v[114:117], 0
	v_mfma_f32_32x32x16_bf16 v[82:97], v[8:11], v[118:121], v[82:97]
	ds_read_b128 v[4:7], v2 offset:64
	ds_read_b128 v[8:11], v2 offset:96
	s_waitcnt lgkmcnt(2)
	v_mfma_f32_32x32x16_bf16 v[98:113], v[12:15], v[118:121], v[98:113]
	s_waitcnt lgkmcnt(1)
	v_mfma_f32_32x32x16_bf16 v[82:97], v[4:7], v[122:125], v[82:97]
	ds_read_b128 v[4:7], v2 offset:8768
	ds_read_b128 v[12:15], v2 offset:8800
	s_waitcnt lgkmcnt(1)
	v_mfma_f32_32x32x16_bf16 v[98:113], v[4:7], v[122:125], v[98:113]
	v_mfma_f32_32x32x16_bf16 v[82:97], v[8:11], v[126:129], v[82:97]
	ds_read_b128 v[4:7], v2 offset:128
	ds_read_b128 v[8:11], v2 offset:160
	s_waitcnt lgkmcnt(2)
	v_mfma_f32_32x32x16_bf16 v[98:113], v[12:15], v[126:129], v[98:113]
	s_waitcnt lgkmcnt(1)
	v_mfma_f32_32x32x16_bf16 v[82:97], v[4:7], v[130:133], v[82:97]
	ds_read_b128 v[4:7], v2 offset:8832
	ds_read_b128 v[12:15], v2 offset:8864
	s_waitcnt lgkmcnt(1)
	v_mfma_f32_32x32x16_bf16 v[98:113], v[4:7], v[130:133], v[98:113]
	v_mfma_f32_32x32x16_bf16 v[82:97], v[8:11], v[134:137], v[82:97]
	ds_read_b128 v[4:7], v2 offset:192
	ds_read_b128 v[8:11], v2 offset:224
	s_waitcnt lgkmcnt(2)
	v_mfma_f32_32x32x16_bf16 v[98:113], v[12:15], v[134:137], v[98:113]
	s_waitcnt lgkmcnt(1)
	v_mfma_f32_32x32x16_bf16 v[82:97], v[4:7], v[138:141], v[82:97]
	ds_read_b128 v[4:7], v2 offset:8896
	ds_read_b128 v[12:15], v2 offset:8928
	s_waitcnt lgkmcnt(1)
	v_mfma_f32_32x32x16_bf16 v[98:113], v[4:7], v[138:141], v[98:113]
	v_mfma_f32_32x32x16_bf16 v[82:97], v[8:11], v[142:145], v[82:97]
	s_waitcnt lgkmcnt(0)
	v_mfma_f32_32x32x16_bf16 v[98:113], v[12:15], v[142:145], v[98:113]
	s_setprio 0
	v_cmp_le_i32_e32 vcc, s38, v162
	v_cmp_lt_i32_e64 s[6:7], s55, v242
	v_cmp_gt_i32_e64 s[4:5], s67, v242
	s_and_b64 s[6:7], vcc, s[6:7]
	v_add_f32_e32 v2, 0x41000000, v249
	s_and_saveexec_b64 s[18:19], s[6:7]
	s_xor_b64 s[6:7], exec, s[18:19]
	s_cbranch_execz .LBB0_2273
	s_cmp_eq_u64 s[6:7], 0
	s_cbranch_scc1 .Lfast_cmp1
	s_nop 2
	v_max_f32_e32 v4, v98, v98
	v_max_f32_e32 v5, v82, v82
	v_max_f32_e32 v4, v5, v4
	v_max3_f32 v4, v4, v83, v99
	s_nop 0
	v_max3_f32 v4, v4, v84, v100
	s_nop 0
	v_max3_f32 v4, v4, v85, v101
	s_nop 0
	v_max3_f32 v4, v4, v86, v102
	s_nop 0
	v_max3_f32 v4, v4, v87, v103
	s_nop 0
	v_max3_f32 v4, v4, v88, v104
	s_nop 0
	v_max3_f32 v4, v4, v89, v105
	s_nop 0
	v_max3_f32 v4, v4, v90, v106
	s_nop 0
	v_max3_f32 v4, v4, v91, v107
	s_nop 0
	v_max3_f32 v4, v4, v92, v108
	s_nop 0
	v_max3_f32 v4, v4, v93, v109
	s_nop 0
	v_max3_f32 v4, v4, v94, v110
	s_nop 0
	v_max3_f32 v4, v4, v95, v111
	s_nop 0
	v_max3_f32 v4, v4, v96, v112
	s_nop 0
	v_max3_f32 v4, v4, v97, v113
	s_nop 0
	v_mov_b32_e32 v5, v4
	s_nop 1
	v_permlane32_swap_b32_e32 v4, v5
	v_max_f32_e32 v5, v5, v5
	v_max_f32_e32 v4, v4, v4
	v_max_f32_e32 v4, v4, v5
	v_mul_f32_e32 v4, 0x3e0293ee, v4
	v_cmp_gt_f32_e32 vcc, v4, v2
	s_nop 1
	v_cndmask_b32_e32 v250, v249, v4, vcc
	v_sub_f32_e32 v2, v249, v250
	v_exp_f32_e32 v2, v2
	s_nop 0
	v_cmp_neq_f32_e32 vcc, 1.0, v2
	s_cbranch_vccz .LBB0_2272
	v_pk_mul_f32 v[80:81], v[80:81], v[2:3] op_sel_hi:[1,0]
	v_pk_mul_f32 v[78:79], v[78:79], v[2:3] op_sel_hi:[1,0]
	v_pk_mul_f32 v[76:77], v[76:77], v[2:3] op_sel_hi:[1,0]
	v_pk_mul_f32 v[74:75], v[74:75], v[2:3] op_sel_hi:[1,0]
	v_pk_mul_f32 v[72:73], v[72:73], v[2:3] op_sel_hi:[1,0]
	v_pk_mul_f32 v[70:71], v[70:71], v[2:3] op_sel_hi:[1,0]
	v_pk_mul_f32 v[68:69], v[68:69], v[2:3] op_sel_hi:[1,0]
	v_pk_mul_f32 v[66:67], v[66:67], v[2:3] op_sel_hi:[1,0]
	v_pk_mul_f32 v[64:65], v[64:65], v[2:3] op_sel_hi:[1,0]
	v_pk_mul_f32 v[62:63], v[62:63], v[2:3] op_sel_hi:[1,0]
	v_pk_mul_f32 v[60:61], v[60:61], v[2:3] op_sel_hi:[1,0]
	v_pk_mul_f32 v[58:59], v[58:59], v[2:3] op_sel_hi:[1,0]
	v_pk_mul_f32 v[56:57], v[56:57], v[2:3] op_sel_hi:[1,0]
	v_pk_mul_f32 v[54:55], v[54:55], v[2:3] op_sel_hi:[1,0]
	v_pk_mul_f32 v[52:53], v[52:53], v[2:3] op_sel_hi:[1,0]
	v_pk_mul_f32 v[50:51], v[50:51], v[2:3] op_sel_hi:[1,0]
	v_pk_mul_f32 v[48:49], v[48:49], v[2:3] op_sel_hi:[1,0]
	v_pk_mul_f32 v[46:47], v[46:47], v[2:3] op_sel_hi:[1,0]
	v_pk_mul_f32 v[44:45], v[44:45], v[2:3] op_sel_hi:[1,0]
	v_pk_mul_f32 v[42:43], v[42:43], v[2:3] op_sel_hi:[1,0]
	v_pk_mul_f32 v[40:41], v[40:41], v[2:3] op_sel_hi:[1,0]
	v_pk_mul_f32 v[38:39], v[38:39], v[2:3] op_sel_hi:[1,0]
	v_pk_mul_f32 v[36:37], v[36:37], v[2:3] op_sel_hi:[1,0]
	v_pk_mul_f32 v[34:35], v[34:35], v[2:3] op_sel_hi:[1,0]
	v_pk_mul_f32 v[32:33], v[32:33], v[2:3] op_sel_hi:[1,0]
	v_pk_mul_f32 v[30:31], v[30:31], v[2:3] op_sel_hi:[1,0]
	v_pk_mul_f32 v[28:29], v[28:29], v[2:3] op_sel_hi:[1,0]
	v_pk_mul_f32 v[26:27], v[26:27], v[2:3] op_sel_hi:[1,0]
	v_pk_mul_f32 v[24:25], v[24:25], v[2:3] op_sel_hi:[1,0]
	v_pk_mul_f32 v[22:23], v[22:23], v[2:3] op_sel_hi:[1,0]
	v_pk_mul_f32 v[20:21], v[20:21], v[2:3] op_sel_hi:[1,0]
	v_pk_mul_f32 v[18:19], v[18:19], v[2:3] op_sel_hi:[1,0]

; template <int MODE, int DK, bool PASS2> ...
;     ...
;             bool selbit = true;
;             if (MODE == M_SLC) {
;                 selbit = ((((const LAS unsigned*)impw)[j >> 5] >> (j & 31)) & 1u) != 0u;
;                 active = active && (__builtin_amdgcn_ballot_w64(selbit) != 0ull);
;             }
;             if (active) {
;                 f32x16 s0, s1;
;                 if (MODE == M_FOX) {
;                     const LAS float* ct = (const LAS float*)(lds + F_CT + buf * 256) + 8 * g;
; #pragma unroll
;                     for (int q4 = 0; q4 < 4; ++q4) {
;                         const f32x4 a = *(const LAS f32x4*)(ct + (q4 >> 1) * 16 + (q4 & 1) * 4), b = *(const LAS f32x4*)(ct + 32 + (q4 >> 1) * 16 + (q4 & 1) * 4);
; #pragma unroll
;                         for (int e = 0; e < 4; ++e) { s0[q4 * 4 + e] = a[e]; s1[q4 * 4 + e] = b[e]; }
;                     }
;                 } else { s0 = (f32x16)(0.f); s1 = (f32x16)(0.f); }
;                 const LAS unsigned char* kb = lds + F_KB0 + buf * F_KBS + g * 16 + prow * KSTR;
;                 __builtin_amdgcn_s_setprio(1);
; #pragma unroll
;                 for (int kk = 0; kk < DK / 16; ++kk) {
;                     const bf16x8 a0 = *(const LAS bf16x8*)(kb + kk * 32);
;                     const bf16x8 a1 = *(const LAS bf16x8*)(kb + 32 * KSTR + kk * 32);
;                     s0 = mfma32(a0, qf[kk], s0); s1 = mfma32(a1, qf[kk], s1);
;                 }
;                 __builtin_amdgcn_s_setprio(0);
;                 const bool need_causal = pos_max > t_wmin;
;                 const bool need_bias = (MODE != M_FOX) && ((t_wmin - pos_max) < 128);
;                 const bool need_win = (MODE == M_WIN) && (t_wmax - pos_min >= 512);
;                 if (!PASS2 && !(need_causal || need_bias || need_win)) {
;                     float mx = fmaxf(s0[0], s1[0]);
; #pragma unroll
;                     for (int r = 1; r < 16; ++r) mx = fmax3(mx, s0[r], s1[r]);
;                     if (MODE == M_SLC) mx = selbit ? mx : NEG;
;                     mx = xhalf_max(mx);
;                     const float mxs = mx * sl2;
;                     const float mn = (mxs > m_run + 8.0f) ? mxs : m_run;
;                     const float alpha = fexp2(m_run - mn);
;                     m_run = mn;
;                     float nm = -mn;
;                     if (MODE == M_SLC) nm = selbit ? nm : -__builtin_inff();
.Lslc_selhit:
	s_and_b32 s4, s48, 31
	v_lshrrev_b32_e32 v4, s48, v246
	v_bfe_u32 v2, v246, s4, 1
	v_and_b32_e32 v4, 1, v4
	v_cmp_ne_u32_e32 vcc, 0, v2
	v_cmp_eq_u32_e64 s[4:5], 1, v4
	s_cbranch_vccz .LBB0_2610
	s_mul_i32 s6, s74, 0x4400
	s_or_b32 s48, s78, 63
	v_add_u32_e32 v2, s6, v215
	s_setprio 2
	ds_read_b128 v[4:7], v2
	ds_read_b128 v[8:11], v2 offset:32
	s_waitcnt lgkmcnt(1)
	v_mfma_f32_32x32x16_bf16 v[98:113], v[4:7], v[114:117], 0
	ds_read_b128 v[4:7], v2 offset:8704
	ds_read_b128 v[12:15], v2 offset:8736
	s_waitcnt lgkmcnt(1)
	v_mfma_f32_32x32x16_bf16 v[82:97], v[4:7], v[114:117], 0
	v_mfma_f32_32x32x16_bf16 v[98:113], v[8:11], v[118:121], v[98:113]
	ds_read_b128 v[4:7], v2 offset:64
	ds_read_b128 v[8:11], v2 offset:96
	s_waitcnt lgkmcnt(2)
	v_mfma_f32_32x32x16_bf16 v[82:97], v[12:15], v[118:121], v[82:97]
	s_waitcnt lgkmcnt(1)
	v_mfma_f32_32x32x16_bf16 v[98:113], v[4:7], v[122:125], v[98:113]
	ds_read_b128 v[4:7], v2 offset:8768
	ds_read_b128 v[12:15], v2 offset:8800
	s_waitcnt lgkmcnt(1)
	v_mfma_f32_32x32x16_bf16 v[82:97], v[4:7], v[122:125], v[82:97]
	v_mfma_f32_32x32x16_bf16 v[98:113], v[8:11], v[126:129], v[98:113]
	ds_read_b128 v[4:7], v2 offset:128
	ds_read_b128 v[8:11], v2 offset:160
	s_waitcnt lgkmcnt(2)
	v_mfma_f32_32x32x16_bf16 v[82:97], v[12:15], v[126:129], v[82:97]
	s_waitcnt lgkmcnt(1)
	v_mfma_f32_32x32x16_bf16 v[98:113], v[4:7], v[130:133], v[98:113]
	ds_read_b128 v[4:7], v2 offset:8832
	ds_read_b128 v[12:15], v2 offset:8864
	s_waitcnt lgkmcnt(1)
	v_mfma_f32_32x32x16_bf16 v[82:97], v[4:7], v[130:133], v[82:97]
	v_mfma_f32_32x32x16_bf16 v[98:113], v[8:11], v[134:137], v[98:113]
	ds_read_b128 v[4:7], v2 offset:192
	ds_read_b128 v[8:11], v2 offset:224
	s_waitcnt lgkmcnt(2)
	v_mfma_f32_32x32x16_bf16 v[82:97], v[12:15], v[134:137], v[82:97]
	s_waitcnt lgkmcnt(1)
	v_mfma_f32_32x32x16_bf16 v[98:113], v[4:7], v[138:141], v[98:113]
	ds_read_b128 v[4:7], v2 offset:8896
	ds_read_b128 v[12:15], v2 offset:8928
	s_waitcnt lgkmcnt(1)
	v_mfma_f32_32x32x16_bf16 v[82:97], v[4:7], v[138:141], v[82:97]
	v_mfma_f32_32x32x16_bf16 v[98:113], v[8:11], v[142:145], v[98:113]
	s_waitcnt lgkmcnt(0)
	v_mfma_f32_32x32x16_bf16 v[82:97], v[12:15], v[142:145], v[82:97]
	s_setprio 0
	v_min_i32_e32 v2, v199, v207
	v_cmp_gt_i32_e64 s[6:7], s48, v207
	v_cmp_le_i32_e32 vcc, s48, v2
	v_add_f32_e32 v2, 0x41000000, v217
	s_and_saveexec_b64 s[48:49], vcc
	s_xor_b64 s[48:49], exec, s[48:49]
	s_cbranch_execz .LBB0_2603
	s_cmp_eq_u64 s[48:49], 0
	s_cbranch_scc1 .Lfast_slc
	s_nop 3
	v_max_f32_e32 v4, v82, v82
	v_max_f32_e32 v5, v98, v98
	v_max_f32_e32 v4, v5, v4
	v_max3_f32 v4, v4, v99, v83
	s_nop 0
	v_max3_f32 v4, v4, v100, v84
	s_nop 0
	v_max3_f32 v4, v4, v101, v85
	s_nop 0
	v_max3_f32 v4, v4, v102, v86
	s_nop 0
	v_max3_f32 v4, v4, v103, v87
	s_nop 0
	v_max3_f32 v4, v4, v104, v88
	s_nop 0
	v_max3_f32 v4, v4, v105, v89
	s_nop 0
	v_max3_f32 v4, v4, v106, v90
	s_nop 0
	v_max3_f32 v4, v4, v107, v91
	s_nop 0
	v_max3_f32 v4, v4, v108, v92
	s_nop 0
	v_max3_f32 v4, v4, v109, v93
	s_nop 0
	v_max3_f32 v4, v4, v110, v94
	s_nop 0
	v_max3_f32 v4, v4, v111, v95
	s_nop 0
	v_max3_f32 v4, v4, v112, v96
	s_nop 0
	v_max3_f32 v4, v4, v113, v97
	s_nop 0
	v_cndmask_b32_e64 v4, v194, v4, s[4:5]
	v_mov_b32_e32 v5, v4
	s_nop 1
	v_permlane32_swap_b32_e32 v4, v5
	v_max_f32_e32 v5, v5, v5
	v_max_f32_e32 v4, v4, v4
	v_max_f32_e32 v4, v4, v5
	v_mul_f32_e32 v4, 0x3e0293ee, v4
	v_cmp_gt_f32_e32 vcc, v4, v2
	s_nop 1
	v_cndmask_b32_e32 v218, v217, v4, vcc
	v_sub_f32_e32 v2, v217, v218
	v_exp_f32_e32 v2, v2
	s_nop 0
	v_cmp_neq_f32_e32 vcc, 1.0, v2
	s_cbranch_vccz .LBB0_2602
	v_pk_mul_f32 v[80:81], v[80:81], v[2:3] op_sel_hi:[1,0]
	v_pk_mul_f32 v[78:79], v[78:79], v[2:3] op_sel_hi:[1,0]
	v_pk_mul_f32 v[76:77], v[76:77], v[2:3] op_sel_hi:[1,0]
	v_pk_mul_f32 v[74:75], v[74:75], v[2:3] op_sel_hi:[1,0]
	v_pk_mul_f32 v[72:73], v[72:73], v[2:3] op_sel_hi:[1,0]
	v_pk_mul_f32 v[70:71], v[70:71], v[2:3] op_sel_hi:[1,0]
	v_pk_mul_f32 v[68:69], v[68:69], v[2:3] op_sel_hi:[1,0]
	v_pk_mul_f32 v[66:67], v[66:67], v[2:3] op_sel_hi:[1,0]
	v_pk_mul_f32 v[64:65], v[64:65], v[2:3] op_sel_hi:[1,0]
	v_pk_mul_f32 v[62:63], v[62:63], v[2:3] op_sel_hi:[1,0]
	v_pk_mul_f32 v[60:61], v[60:61], v[2:3] op_sel_hi:[1,0]
	v_pk_mul_f32 v[58:59], v[58:59], v[2:3] op_sel_hi:[1,0]
	v_pk_mul_f32 v[56:57], v[56:57], v[2:3] op_sel_hi:[1,0]
	v_pk_mul_f32 v[54:55], v[54:55], v[2:3] op_sel_hi:[1,0]
	v_pk_mul_f32 v[52:53], v[52:53], v[2:3] op_sel_hi:[1,0]
	v_pk_mul_f32 v[50:51], v[50:51], v[2:3] op_sel_hi:[1,0]
	v_pk_mul_f32 v[48:49], v[48:49], v[2:3] op_sel_hi:[1,0]
	v_pk_mul_f32 v[46:47], v[46:47], v[2:3] op_sel_hi:[1,0]
	v_pk_mul_f32 v[44:45], v[44:45], v[2:3] op_sel_hi:[1,0]
	v_pk_mul_f32 v[42:43], v[42:43], v[2:3] op_sel_hi:[1,0]
	v_pk_mul_f32 v[40:41], v[40:41], v[2:3] op_sel_hi:[1,0]
	v_pk_mul_f32 v[38:39], v[38:39], v[2:3] op_sel_hi:[1,0]
	v_pk_mul_f32 v[36:37], v[36:37], v[2:3] op_sel_hi:[1,0]
	v_pk_mul_f32 v[34:35], v[34:35], v[2:3] op_sel_hi:[1,0]
	v_pk_mul_f32 v[32:33], v[32:33], v[2:3] op_sel_hi:[1,0]
	v_pk_mul_f32 v[30:31], v[30:31], v[2:3] op_sel_hi:[1,0]
	v_pk_mul_f32 v[28:29], v[28:29], v[2:3] op_sel_hi:[1,0]
	v_pk_mul_f32 v[26:27], v[26:27], v[2:3] op_sel_hi:[1,0]
	v_pk_mul_f32 v[24:25], v[24:25], v[2:3] op_sel_hi:[1,0]
	v_pk_mul_f32 v[22:23], v[22:23], v[2:3] op_sel_hi:[1,0]
	v_pk_mul_f32 v[20:21], v[20:21], v[2:3] op_sel_hi:[1,0]
	v_pk_mul_f32 v[18:19], v[18:19], v[2:3] op_sel_hi:[1,0]
